# attention QK^T block: K-fragment LDS reads pipelined 6 deep (two base addresses + immediates, freed address registers as buffers), accumulators in place
# speedup vs baseline: 1.0218x; 1.0053x over previous
; __device__ __forceinline__ void attn_item(const Params& p, int l, int bh, int qt, char* lds) {
;     ...
;     if (active) {
; #pragma unroll
;       for (int qs = 0; qs < 2; qs++)
; #pragma unroll
;         for (int ks = 0; ks < 4; ks++) sc[qs][ks] = (f32x4){0.f, 0.f, 0.f, 0.f};
; #pragma unroll
;       for (int ks = 0; ks < 4; ks++)
; #pragma unroll
;         for (int kc = 0; kc < 6; kc++) {
;           const int krow_ = ks * 16 + fr, kcl_ = kc * 4 + fq;
;           const bf16x8 kf = *(const bf16x8*)(kb + (krow_ * 24 + ((kcl_ & ~7) | ((kcl_ & 7) ^ ((krow_ >> 1) & 7)))) * 16);
;           sc[0][ks] = __builtin_amdgcn_mfma_f32_16x16x32_bf16(kf, qf[0][kc], sc[0][ks], 0, 0, 0);
;           sc[1][ks] = __builtin_amdgcn_mfma_f32_16x16x32_bf16(kf, qf[1][kc], sc[1][ks], 0, 0, 0);
;           if (kc & 1) __builtin_amdgcn_sched_barrier(0);
;         }
;     }
.LBB0_443:
	s_bitcmp1_b32 s2, 0
	s_cselect_b32 s3, 0x6000, 0
	s_add_i32 s3, s3, 0
	v_add_u32_e32 v240, s3, v184
	v_add_u32_e32 v241, s3, v185
	ds_read_b128 v[150:153], v240
	ds_read_b128 v[154:157], v241
	ds_read_b128 v[186:189], v240 offset:128
	ds_read_b128 v[190:193], v241 offset:128
	ds_read_b128 v[194:197], v240 offset:256
	ds_read_b128 v[232:235], v241 offset:256
	s_waitcnt lgkmcnt(5)
	v_mfma_f32_16x16x32_bf16 v[116:119], v[150:153], v[36:39], 0
	v_mfma_f32_16x16x32_bf16 v[124:127], v[150:153], v[60:63], 0
	ds_read_b128 v[236:239], v240 offset:6144
	s_waitcnt lgkmcnt(5)
	v_mfma_f32_16x16x32_bf16 v[116:119], v[154:157], v[40:43], v[116:119]
	v_mfma_f32_16x16x32_bf16 v[124:127], v[154:157], v[64:67], v[124:127]
	ds_read_b128 v[150:153], v241 offset:6144
	s_waitcnt lgkmcnt(5)
	v_mfma_f32_16x16x32_bf16 v[116:119], v[186:189], v[44:47], v[116:119]
	v_mfma_f32_16x16x32_bf16 v[124:127], v[186:189], v[68:71], v[124:127]
	ds_read_b128 v[154:157], v240 offset:6272
	s_waitcnt lgkmcnt(5)
	v_mfma_f32_16x16x32_bf16 v[116:119], v[190:193], v[48:51], v[116:119]
	v_mfma_f32_16x16x32_bf16 v[124:127], v[190:193], v[72:75], v[124:127]
	ds_read_b128 v[186:189], v241 offset:6272
	s_waitcnt lgkmcnt(5)
	v_mfma_f32_16x16x32_bf16 v[116:119], v[194:197], v[52:55], v[116:119]
	v_mfma_f32_16x16x32_bf16 v[124:127], v[194:197], v[76:79], v[124:127]
	ds_read_b128 v[190:193], v240 offset:6400
	s_waitcnt lgkmcnt(5)
	v_mfma_f32_16x16x32_bf16 v[116:119], v[232:235], v[56:59], v[116:119]
	v_mfma_f32_16x16x32_bf16 v[124:127], v[232:235], v[80:83], v[124:127]
	ds_read_b128 v[194:197], v241 offset:6400
	s_waitcnt lgkmcnt(5)
	v_mfma_f32_16x16x32_bf16 v[120:123], v[236:239], v[36:39], 0
	v_mfma_f32_16x16x32_bf16 v[128:131], v[236:239], v[60:63], 0
	ds_read_b128 v[232:235], v240 offset:12288
	s_waitcnt lgkmcnt(5)
	v_mfma_f32_16x16x32_bf16 v[120:123], v[150:153], v[40:43], v[120:123]
	v_mfma_f32_16x16x32_bf16 v[128:131], v[150:153], v[64:67], v[128:131]
	ds_read_b128 v[236:239], v241 offset:12288
	s_waitcnt lgkmcnt(5)
	v_mfma_f32_16x16x32_bf16 v[120:123], v[154:157], v[44:47], v[120:123]
	v_mfma_f32_16x16x32_bf16 v[128:131], v[154:157], v[68:71], v[128:131]
	ds_read_b128 v[150:153], v240 offset:12416
	s_waitcnt lgkmcnt(5)
	v_mfma_f32_16x16x32_bf16 v[120:123], v[186:189], v[48:51], v[120:123]
	v_mfma_f32_16x16x32_bf16 v[128:131], v[186:189], v[72:75], v[128:131]
	ds_read_b128 v[154:157], v241 offset:12416
	s_waitcnt lgkmcnt(5)
	v_mfma_f32_16x16x32_bf16 v[120:123], v[190:193], v[52:55], v[120:123]
	v_mfma_f32_16x16x32_bf16 v[128:131], v[190:193], v[76:79], v[128:131]
	ds_read_b128 v[186:189], v240 offset:12544
	s_waitcnt lgkmcnt(5)
	v_mfma_f32_16x16x32_bf16 v[120:123], v[194:197], v[56:59], v[120:123]
	v_mfma_f32_16x16x32_bf16 v[128:131], v[194:197], v[80:83], v[128:131]
	ds_read_b128 v[190:193], v241 offset:12544
	s_waitcnt lgkmcnt(5)
	v_mfma_f32_16x16x32_bf16 v[140:143], v[232:235], v[36:39], 0
	v_mfma_f32_16x16x32_bf16 v[132:135], v[232:235], v[60:63], 0
	ds_read_b128 v[194:197], v240 offset:18432
	s_waitcnt lgkmcnt(5)
	v_mfma_f32_16x16x32_bf16 v[140:143], v[236:239], v[40:43], v[140:143]
	v_mfma_f32_16x16x32_bf16 v[132:135], v[236:239], v[64:67], v[132:135]
	ds_read_b128 v[232:235], v241 offset:18432
	s_waitcnt lgkmcnt(5)
	v_mfma_f32_16x16x32_bf16 v[140:143], v[150:153], v[44:47], v[140:143]
	v_mfma_f32_16x16x32_bf16 v[132:135], v[150:153], v[68:71], v[132:135]
	ds_read_b128 v[236:239], v240 offset:18560
	s_waitcnt lgkmcnt(5)
	v_mfma_f32_16x16x32_bf16 v[140:143], v[154:157], v[48:51], v[140:143]
	v_mfma_f32_16x16x32_bf16 v[132:135], v[154:157], v[72:75], v[132:135]
	ds_read_b128 v[150:153], v241 offset:18560
	s_waitcnt lgkmcnt(5)
	v_mfma_f32_16x16x32_bf16 v[140:143], v[186:189], v[52:55], v[140:143]
	v_mfma_f32_16x16x32_bf16 v[132:135], v[186:189], v[76:79], v[132:135]
	ds_read_b128 v[154:157], v240 offset:18688
	s_waitcnt lgkmcnt(5)
	v_mfma_f32_16x16x32_bf16 v[140:143], v[190:193], v[56:59], v[140:143]
	v_mfma_f32_16x16x32_bf16 v[132:135], v[190:193], v[80:83], v[132:135]
	ds_read_b128 v[186:189], v241 offset:18688
	s_waitcnt lgkmcnt(5)
	v_mfma_f32_16x16x32_bf16 v[144:147], v[194:197], v[36:39], 0
	v_mfma_f32_16x16x32_bf16 v[136:139], v[194:197], v[60:63], 0
	s_waitcnt lgkmcnt(4)
	v_mfma_f32_16x16x32_bf16 v[144:147], v[232:235], v[40:43], v[144:147]
	v_mfma_f32_16x16x32_bf16 v[136:139], v[232:235], v[64:67], v[136:139]
	s_waitcnt lgkmcnt(3)
	v_mfma_f32_16x16x32_bf16 v[144:147], v[236:239], v[44:47], v[144:147]
	v_mfma_f32_16x16x32_bf16 v[136:139], v[236:239], v[68:71], v[136:139]
	s_waitcnt lgkmcnt(2)
	v_mfma_f32_16x16x32_bf16 v[144:147], v[150:153], v[48:51], v[144:147]
	v_mfma_f32_16x16x32_bf16 v[136:139], v[150:153], v[72:75], v[136:139]
	s_waitcnt lgkmcnt(1)
	v_mfma_f32_16x16x32_bf16 v[144:147], v[154:157], v[52:55], v[144:147]
	v_mfma_f32_16x16x32_bf16 v[136:139], v[154:157], v[76:79], v[136:139]
	s_waitcnt lgkmcnt(0)
	v_mfma_f32_16x16x32_bf16 v[144:147], v[186:189], v[56:59], v[144:147]
	v_mfma_f32_16x16x32_bf16 v[136:139], v[186:189], v[80:83], v[136:139]
	s_cmp_lt_u32 s2, s97
	s_cbranch_scc1 .LBB0_445
; __device__ __forceinline__ void attn_item(const Params& p, int l, int bh, int qt, char* lds) {
;     ...
;     if (active) {
;       if (kt >= nkt - 2) {
; #pragma unroll
;         for (int qs = 0; qs < 2; qs++) {
;           const int qrow = q0 + wid * 32 + qs * 16 + fr;
; #pragma unroll
;           for (int ks = 0; ks < 4; ks++)
; #pragma unroll
;             for (int j = 0; j < 4; j++) { const int key = k0 + ks * 16 + fq * 4 + j; if (key > qrow) sc[qs][ks][j] = -1e30f; }
;         }
;       }
	s_nop 2
	v_add_u32_e32 v150, s66, v174
	v_mov_b32_e32 v2, s75
	v_cmp_gt_i32_e32 vcc, v150, v180
	v_cmp_lt_i32_e64 s[36:37], v150, v180
	v_add_u32_e32 v151, 2, v150
	v_cndmask_b32_e32 v2, v116, v2, vcc
	v_cndmask_b32_e64 v116, v2, v116, s[36:37]
	v_cndmask_b32_e64 v117, v231, v117, s[36:37]
	v_cmp_le_i32_e64 s[36:37], v151, v180
	v_add_u32_e32 v152, 3, v150
	v_add_u32_e32 v153, 16, v150
	v_cndmask_b32_e64 v118, v231, v118, s[36:37]
	v_cmp_le_i32_e64 s[36:37], v152, v180
	v_mov_b32_e32 v2, s75
	v_add_u32_e32 v154, 18, v150
	v_cndmask_b32_e64 v119, v231, v119, s[36:37]
	v_cmp_gt_i32_e64 s[36:37], v153, v180
	v_add_u32_e32 v153, 17, v150
	v_add_u32_e32 v155, 19, v150
	v_cndmask_b32_e64 v120, v120, v2, s[36:37]
	v_cmp_le_i32_e64 s[36:37], v153, v180
	v_add_u32_e32 v156, 32, v150
	v_add_u32_e32 v157, 33, v150
	v_cndmask_b32_e64 v121, v231, v121, s[36:37]
	v_cmp_le_i32_e64 s[36:37], v154, v180
	v_add_u32_e32 v158, 34, v150
	v_add_u32_e32 v159, 35, v150
	v_cndmask_b32_e64 v122, v231, v122, s[36:37]
	v_cmp_le_i32_e64 s[36:37], v155, v180
	v_add_u32_e32 v160, 48, v150
	v_add_u32_e32 v161, 49, v150
	v_cndmask_b32_e64 v123, v231, v123, s[36:37]
	v_cmp_gt_i32_e64 s[36:37], v156, v180
	v_add_u32_e32 v162, 50, v150
	v_add_u32_e32 v163, 51, v150
	v_cndmask_b32_e64 v140, v140, v2, s[36:37]
	v_cmp_le_i32_e64 s[36:37], v157, v180
	s_nop 1
	v_cndmask_b32_e64 v141, v231, v141, s[36:37]
	v_cmp_le_i32_e64 s[36:37], v158, v180
	s_nop 1
	v_cndmask_b32_e64 v142, v231, v142, s[36:37]
	v_cmp_le_i32_e64 s[36:37], v159, v180
	s_nop 1
	v_cndmask_b32_e64 v143, v231, v143, s[36:37]
	v_cmp_gt_i32_e64 s[36:37], v160, v180
	s_nop 1
	v_cndmask_b32_e64 v144, v144, v2, s[36:37]
	v_cmp_le_i32_e64 s[36:37], v161, v180
	s_nop 1
	v_cndmask_b32_e64 v145, v231, v145, s[36:37]
	v_cmp_le_i32_e64 s[36:37], v162, v180
	s_nop 1
	v_cndmask_b32_e64 v146, v231, v146, s[36:37]
	v_cmp_le_i32_e64 s[36:37], v163, v180
	s_nop 1
	v_cndmask_b32_e64 v147, v231, v147, s[36:37]
	v_cmp_gt_i32_e64 s[36:37], v150, v242
	s_nop 1
	v_cndmask_b32_e64 v2, v124, v2, s[36:37]
	v_cmp_lt_i32_e64 s[36:37], v150, v242
	s_nop 1
	v_cndmask_b32_e64 v124, v2, v124, s[36:37]
	v_mov_b32_e32 v2, s75
	v_cndmask_b32_e32 v128, v128, v2, vcc
	v_cmp_le_i32_e32 vcc, v153, v242
	v_cndmask_b32_e64 v125, v231, v125, s[36:37]
	v_cmp_le_i32_e64 s[36:37], v151, v242
	v_cndmask_b32_e32 v129, v231, v129, vcc
	v_cmp_le_i32_e32 vcc, v154, v242
	v_cndmask_b32_e64 v126, v231, v126, s[36:37]
	v_cmp_le_i32_e64 s[36:37], v152, v242
	v_cndmask_b32_e32 v130, v231, v130, vcc
	v_cmp_le_i32_e32 vcc, v155, v242
	v_cndmask_b32_e64 v127, v231, v127, s[36:37]
	s_nop 0
	v_cndmask_b32_e32 v131, v231, v131, vcc
	v_cmp_gt_i32_e32 vcc, v156, v242
	s_nop 1
	v_cndmask_b32_e32 v132, v132, v2, vcc
	v_cmp_le_i32_e32 vcc, v157, v242
	s_nop 1
	v_cndmask_b32_e32 v133, v231, v133, vcc
	v_cmp_le_i32_e32 vcc, v158, v242
	s_nop 1
	v_cndmask_b32_e32 v134, v231, v134, vcc
	v_cmp_le_i32_e32 vcc, v159, v242
	s_nop 1
	v_cndmask_b32_e32 v135, v231, v135, vcc
	v_cmp_gt_i32_e32 vcc, v160, v242
	s_nop 1
	v_cndmask_b32_e32 v136, v136, v2, vcc
	v_cmp_le_i32_e32 vcc, v161, v242
	s_nop 1
	v_cndmask_b32_e32 v137, v231, v137, vcc
	v_cmp_le_i32_e32 vcc, v162, v242
	s_nop 1
	v_cndmask_b32_e32 v138, v231, v138, vcc
	v_cmp_le_i32_e32 vcc, v163, v242
	s_nop 1
	v_cndmask_b32_e32 v139, v231, v139, vcc
